# norm phase 2 (pre-FFN) row loop: the 9 serialized adaLN/gamma parameter loads issued up front, same as norm 1
# baseline (speedup 1.0000x reference)
; DI unsigned pack2(float a, float b) { f2_t v = {a, b}; return __builtin_bit_cast(unsigned, __builtin_convertvector(v, bf2_t)); }
; DI int otid() { int t = threadIdx.x; asm volatile("" : "+v"(t)); return t; }
; template <int MODE>
; DI void phase_norm(const float* xin, const float* g, const float* modl, int sh_off, int sc_off, u16* hout, float* fout) {
;   const int tid = otid(); const int lane = tid & 63, w = tid >> 6;
;   for (int row = blockIdx.x * NWAVE + w; row < NTOK; row += gridDim.x * NWAVE) {
;     const int b = row >> 14;
;     const float4* xr = (const float4*)(xin + (size_t)row * 1024);
;     float4 v[4];
; #pragma unroll
;     for (int i = 0; i < 4; ++i) v[i] = xr[lane + i * 64];
;     float ss = 0.f;
; #pragma unroll
;     for (int i = 0; i < 4; ++i) ss += v[i].x * v[i].x + v[i].y * v[i].y + v[i].z * v[i].z + v[i].w * v[i].w;
;     ss = wave_sum(ss);
;     const float inv = rsqrtf(ss * (1.f / 1024.f) + 1e-6f);
; #pragma unroll
;     for (int i = 0; i < 4; ++i) {
;       const int col = (lane + i * 64) * 4;
;       const float4 g4 = *(const float4*)(g + col);
;       if (MODE == 0) {
;         const float4 sc4 = *(const float4*)(modl + b * 6144 + sc_off + col);
;         const float4 sh4 = *(const float4*)(modl + b * 6144 + sh_off + col);
;         float y0 = v[i].x * inv * g4.x * (1.f + sc4.x) + sh4.x;
;         float y1 = v[i].y * inv * g4.y * (1.f + sc4.y) + sh4.y;
;         float y2 = v[i].z * inv * g4.z * (1.f + sc4.z) + sh4.z;
;         float y3 = v[i].w * inv * g4.w * (1.f + sc4.w) + sh4.w;
;         *(uint2*)(hout + (size_t)row * 1024 + col) = make_uint2(pack2(y0, y1), pack2(y2, y3));
.LBB0_597:
	v_ashrrev_i32_e32 v3, 31, v2
	v_lshlrev_b64 v[32:33], 12, v[2:3]
	v_lshl_add_u64 v[44:45], v[6:7], 0, v[32:33]
	global_load_dwordx4 v[32:35], v[44:45], off
	global_load_dwordx4 v[36:39], v[44:45], off offset:1024
	global_load_dwordx4 v[40:43], v[44:45], off offset:2048
	s_nop 0
	global_load_dwordx4 v[44:47], v[44:45], off offset:3072
	v_ashrrev_i32_e32 v11, 14, v2
	v_mul_i32_i24_e32 v48, 0x1800, v11
	v_ashrrev_i32_e32 v49, 31, v48
	v_lshl_add_u64 v[56:57], v[48:49], 2, s[24:25]
	s_mov_b64 s[6:7], 0x4000
	v_lshl_add_u64 v[60:61], v[56:57], 0, s[6:7]
	s_mov_b64 s[6:7], 0x3000
	v_lshl_add_u64 v[48:49], v[60:61], 0, v[0:1]
	v_lshl_add_u64 v[62:63], v[56:57], 0, s[6:7]
	global_load_dwordx4 v[48:51], v[48:49], off
	s_nop 0
	global_load_dwordx4 v[52:55], v[4:5], off
	v_lshl_add_u64 v[56:57], v[62:63], 0, v[0:1]
	global_load_dwordx4 v[56:59], v[56:57], off
	v_mov_b32_e32 v128, v10
	v_mov_b32_e32 v129, v1
	v_mov_b32_e32 v130, v12
	v_mov_b32_e32 v131, v1
	v_mov_b32_e32 v132, v14
	v_mov_b32_e32 v133, v1
	v_lshl_add_u64 v[134:135], v[60:61], 0, v[128:129]
	v_lshl_add_u64 v[136:137], v[62:63], 0, v[128:129]
	v_lshl_add_u64 v[138:139], v[60:61], 0, v[130:131]
	v_lshl_add_u64 v[140:141], v[62:63], 0, v[130:131]
	v_lshl_add_u64 v[142:143], v[60:61], 0, v[132:133]
	v_lshl_add_u64 v[144:145], v[62:63], 0, v[132:133]
	global_load_dwordx4 v[86:89], v[4:5], off offset:1024
	global_load_dwordx4 v[90:93], v[134:135], off
	global_load_dwordx4 v[94:97], v[136:137], off
	global_load_dwordx4 v[98:101], v[4:5], off offset:2048
	global_load_dwordx4 v[102:105], v[138:139], off
	global_load_dwordx4 v[106:109], v[140:141], off
	global_load_dwordx4 v[110:113], v[4:5], off offset:3072
	global_load_dwordx4 v[114:117], v[142:143], off
	global_load_dwordx4 v[118:121], v[144:145], off
	s_waitcnt vmcnt(15)
	v_mov_b32_e32 v70, v33
	s_waitcnt vmcnt(14)
	v_mov_b32_e32 v71, v37
	v_mov_b32_e32 v68, v32
	v_mov_b32_e32 v69, v36
	s_waitcnt vmcnt(13)
	v_mov_b32_e32 v78, v41
	s_waitcnt vmcnt(12)
	v_mov_b32_e32 v79, v45
	v_pk_mul_f32 v[70:71], v[70:71], v[70:71]
	v_mov_b32_e32 v64, v34
	v_mov_b32_e32 v65, v38
	v_mov_b32_e32 v76, v40
	v_mov_b32_e32 v77, v44
	v_pk_mul_f32 v[78:79], v[78:79], v[78:79]
	v_pk_fma_f32 v[68:69], v[68:69], v[68:69], v[70:71]
	v_mov_b32_e32 v66, v35
	v_mov_b32_e32 v67, v39
	v_mov_b32_e32 v72, v42
	v_mov_b32_e32 v73, v46
	v_pk_fma_f32 v[70:71], v[76:77], v[76:77], v[78:79]
	v_pk_fma_f32 v[64:65], v[64:65], v[64:65], v[68:69]
	v_mov_b32_e32 v74, v43
	v_mov_b32_e32 v75, v47
	v_pk_fma_f32 v[68:69], v[72:73], v[72:73], v[70:71]
	v_pk_fma_f32 v[64:65], v[66:67], v[66:67], v[64:65]
	v_pk_fma_f32 v[66:67], v[74:75], v[74:75], v[68:69]
	v_add_f32_e32 v11, v64, v65
	v_add_f32_e32 v11, v11, v66
	v_add_f32_e32 v11, v11, v67
	ds_bpermute_b32 v13, v242, v11
	v_lshlrev_b64 v[64:65], 11, v[2:3]
	s_waitcnt vmcnt(11)
	v_pk_add_f32 v[48:49], v[48:49], 1.0 op_sel_hi:[1,0]
	v_pk_add_f32 v[50:51], v[50:51], 1.0 op_sel_hi:[1,0]
	v_lshl_add_u64 v[64:65], v[8:9], 0, v[64:65]
	s_waitcnt lgkmcnt(0)
	v_add_f32_e32 v11, v11, v13
	ds_bpermute_b32 v13, v243, v11
	v_add_u32_e32 v2, s3, v2
	s_waitcnt lgkmcnt(0)
	v_add_f32_e32 v11, v11, v13
	ds_bpermute_b32 v13, v244, v11
	s_waitcnt lgkmcnt(0)
	v_add_f32_e32 v11, v11, v13
	ds_bpermute_b32 v13, v245, v11
	s_waitcnt lgkmcnt(0)
	v_add_f32_e32 v11, v11, v13
	ds_bpermute_b32 v13, v246, v11
	s_waitcnt lgkmcnt(0)
	v_add_f32_e32 v13, v11, v13
	ds_bpermute_b32 v15, v247, v13
	v_mov_b32_e32 v11, v1
	v_lshl_add_u64 v[66:67], v[60:61], 0, v[10:11]
	s_waitcnt lgkmcnt(0)
	v_add_f32_e32 v3, v13, v15
	v_fmamk_f32 v3, v3, 0x3a800000, v225
	v_mul_f32_e32 v13, 0x4b800000, v3
	v_cmp_gt_f32_e32 vcc, s33, v3
	v_mov_b32_e32 v15, v1
	s_nop 0
	v_cndmask_b32_e32 v3, v3, v13, vcc
	v_rsq_f32_e32 v3, v3
	s_nop 0
	v_mul_f32_e32 v13, 0x45800000, v3
	v_cndmask_b32_e32 v68, v3, v13, vcc
	v_pk_mul_f32 v[32:33], v[32:33], v[68:69] op_sel_hi:[1,0]
	v_pk_mul_f32 v[34:35], v[34:35], v[68:69] op_sel_hi:[1,0]
	s_waitcnt vmcnt(10)
	v_pk_mul_f32 v[32:33], v[52:53], v[32:33]
	v_pk_mul_f32 v[34:35], v[54:55], v[34:35]
	s_waitcnt vmcnt(0)
	v_pk_fma_f32 v[32:33], v[48:49], v[32:33], v[56:57]
	v_pk_fma_f32 v[34:35], v[50:51], v[34:35], v[58:59]
	v_cvt_pk_bf16_f32 v32, v32, v33
	v_cvt_pk_bf16_f32 v33, v34, v35
	global_store_dwordx2 v[64:65], v[32:33], off
	s_nop 0
	v_lshl_add_u64 v[52:53], v[62:63], 0, v[10:11]
	v_pk_mul_f32 v[36:37], v[36:37], v[68:69] op_sel_hi:[1,0]
	v_pk_mul_f32 v[38:39], v[38:39], v[68:69] op_sel_hi:[1,0]
	v_mov_b32_e32 v13, v1
	v_lshl_add_u64 v[56:57], v[60:61], 0, v[12:13]
	v_pk_mul_f32 v[40:41], v[40:41], v[68:69] op_sel_hi:[1,0]
	v_pk_mul_f32 v[42:43], v[42:43], v[68:69] op_sel_hi:[1,0]
	v_pk_mul_f32 v[44:45], v[44:45], v[68:69] op_sel_hi:[1,0]
	v_pk_mul_f32 v[46:47], v[46:47], v[68:69] op_sel_hi:[1,0]
	v_cmp_lt_i32_e32 vcc, s94, v2
	s_or_b64 s[26:27], vcc, s[26:27]
	v_pk_mul_f32 v[32:33], v[36:37], v[86:87]
	v_pk_add_f32 v[36:37], v[90:91], 1.0 op_sel_hi:[1,0]
	v_pk_mul_f32 v[34:35], v[38:39], v[88:89]
	v_pk_add_f32 v[38:39], v[92:93], 1.0 op_sel_hi:[1,0]
	v_pk_fma_f32 v[32:33], v[32:33], v[36:37], v[94:95]
	v_pk_fma_f32 v[34:35], v[34:35], v[38:39], v[96:97]
	v_cvt_pk_bf16_f32 v32, v32, v33
	v_cvt_pk_bf16_f32 v33, v34, v35
	global_store_dwordx2 v[64:65], v[32:33], off offset:512
	s_nop 0
	v_lshl_add_u64 v[48:49], v[62:63], 0, v[12:13]
	v_lshl_add_u64 v[52:53], v[60:61], 0, v[14:15]
	v_pk_mul_f32 v[32:33], v[40:41], v[98:99]
	v_pk_add_f32 v[36:37], v[102:103], 1.0 op_sel_hi:[1,0]
	v_pk_mul_f32 v[34:35], v[42:43], v[100:101]
	v_pk_add_f32 v[38:39], v[104:105], 1.0 op_sel_hi:[1,0]
	v_pk_fma_f32 v[32:33], v[32:33], v[36:37], v[106:107]
	v_pk_fma_f32 v[34:35], v[34:35], v[38:39], v[108:109]
	v_cvt_pk_bf16_f32 v32, v32, v33
	v_cvt_pk_bf16_f32 v33, v34, v35
	global_store_dwordx2 v[64:65], v[32:33], off offset:1024
	s_nop 0
	v_lshl_add_u64 v[40:41], v[62:63], 0, v[14:15]
	v_pk_mul_f32 v[32:33], v[44:45], v[110:111]
	v_pk_add_f32 v[36:37], v[114:115], 1.0 op_sel_hi:[1,0]
	v_pk_mul_f32 v[34:35], v[46:47], v[112:113]
	v_pk_add_f32 v[38:39], v[116:117], 1.0 op_sel_hi:[1,0]
	v_pk_fma_f32 v[32:33], v[32:33], v[36:37], v[118:119]
	v_pk_fma_f32 v[34:35], v[34:35], v[38:39], v[120:121]
	v_cvt_pk_bf16_f32 v32, v32, v33
	v_cvt_pk_bf16_f32 v33, v34, v35
	global_store_dwordx2 v[64:65], v[32:33], off offset:1536
	s_andn2_b64 exec, exec, s[26:27]
	s_cbranch_execnz .LBB0_597
